# phase 2: odd column groups walk the row-panel groups backwards so the panel group in L2 is reused at each column-group change (on top of v40)
# speedup vs baseline: 1.0025x; 1.0025x over previous
.LBB0_133:
	s_cmp_eq_u32 s99, 0
	s_cbranch_scc1 .Lt2d_adv0
	s_add_u32 s98, s98, 1
	s_cmp_lt_u32 s98, 12
	s_cbranch_scc0 .Lt2d_tail
	s_and_b32 s3, s98, 3
	s_bitcmp1_b32 s98, 2
	s_cbranch_scc0 .Lt2d_fw
	s_sub_u32 s3, 3, s3
.Lt2d_fw:
	s_mul_i32 s3, s3, 0xc8
	s_lshr_b32 vcc_lo, s98, 2
	s_lshl_b32 vcc_lo, vcc_lo, 3
	s_add_u32 s3, s3, vcc_lo
	s_add_u32 s3, s3, s100
	s_branch .Lt2d_advd
